# v13 + separate first-tile / later-tile copies of the peeled K-loop head; later-tile copy does not wait on the previous epilogue's store acks (vmcnt 8 -> 16/24)
# baseline (speedup 1.0000x reference)
; #define PG8_STAGE(bufoff, gbase, voff) do { _Pragma("unroll") for (int _i = 0; _i < 2; ++_i) \
;         __builtin_amdgcn_global_load_lds((const unsigned*)((const char*)(gbase) + (voff)[_i]), (LAS unsigned*)(lds + (bufoff) + ldsw + _i * 8192), 16, 0, 0); } while (0)
; #define PG8_LDA(dst, b, h) do { _Pragma("unroll") for (int m = 0; m < 4; ++m) _Pragma("unroll") for (int k = 0; k < 2; ++k) dst[m][k] = *(const LAS bf16x8*)(lds + PG8_SA(b, h) + aoff + m * 2048 + k * 1024); } while (0)
; #define PG8_LDB(dst, b, h) do { _Pragma("unroll") for (int n = 0; n < 2; ++n) _Pragma("unroll") for (int k = 0; k < 2; ++k) dst[n][k] = *(const LAS bf16x8*)(lds + PG8_SB(b, h) + boff + n * 2048 + k * 1024); } while (0)
; #define PG8_MMA(ai, bj, At, Bt) do { __builtin_amdgcn_s_setprio(1); _Pragma("unroll") for (int m = 0; m < 4; ++m) _Pragma("unroll") for (int n = 0; n < 2; ++n) _Pragma("unroll") for (int k = 0; k < 2; ++k) \
;         acc[ai][bj][m][n] = __builtin_amdgcn_mfma_f32_16x16x32_bf16(Bt[n][k], At[m][k], acc[ai][bj][m][n], 0, 0, 0); __builtin_amdgcn_s_setprio(0); } while (0)
; #define PG8_WAIT_V(n) asm volatile("s_waitcnt vmcnt(" #n ")" ::: "memory")
; template <class Epi, class Sched>
; __device__ __forceinline__ void gemm_phase(LAS unsigned char* lds, const int lda, const int ldb, const int K, const Sched& S, const Epi& E) {
;     ...
;         const bool has_next = S.next(ui + 1, nxt);
;         const char* nA = has_next ? nxt.A : cA; const char* nB = has_next ? nxt.B : cB;
;         for (int t = 0; t < nt; t += 2) {
;             const bool last = (t == nt - 2);
;             const char* a1 = cA + (size_t)(t + 1) * kstep;
;             const char* a2 = last ? nA : cA + (size_t)(t + 2) * kstep; const char* b2 = last ? nB : cB + (size_t)(t + 2) * kstep;
;             const char* a3 = a2 + kstep; const char* b3 = b2 + kstep;
;             PG8_LDB(B0, 0, 0); PG8_LDB(B1, 0, 1); PG8_SCHED; PG8_LDA(At, 0, 0); PG8_STAGE(PG8_SA(1, 1), a1 + hstepA, voffA);
;             PG8_WAIT_V(8); PG8_WAIT_L(0); PG8_BAR; PG8_MMA(0, 0, At, B0); PG8_MMA(0, 1, At, B1); PG8_BAR; PG8_SCHED;
;             PG8_LDA(At, 0, 1); PG8_STAGE(PG8_SB(0, 0), b2, voffB); PG8_STAGE(PG8_SB(0, 1), b2 + hstepB, voffB); PG8_STAGE(PG8_SA(0, 0), a2, voffA);
;             PG8_WAIT_V(8); PG8_WAIT_L(0); PG8_BAR; PG8_MMA(1, 0, At, B0); PG8_MMA(1, 1, At, B1); PG8_BAR; PG8_SCHED;
.LBB0_240:
	s_lshl_b32 s20, s20, 8
	s_ashr_i32 s21, s20, 31
	s_add_u32 s22, s22, 0x40080
	s_addc_u32 s23, s23, 0
	s_add_u32 s13, s24, 0x100
	s_addc_u32 s15, s25, 0
	s_mov_b32 s65, -2
	v_lshl_add_u64 v[214:215], s[20:21], 2, v[204:205]
	v_add_u32_e32 v230, 0x80, v200
	v_add_u32_e32 v231, 0x80, v196
	v_add_u32_e32 v232, 0x80, v202
	v_add_u32_e32 v233, 0x80, v198
	s_cmp_eq_u32 s41, 1
	s_cbranch_scc1 .Lpeel1_first
	s_add_u32 s21, s22, 0xfffc0080
	s_addc_u32 s24, s23, -1
	s_cmp_eq_u32 s65, 12
	s_cselect_b32 s29, s17, s24
	s_cselect_b32 s28, s16, s21
	s_cselect_b32 s31, s19, s15
	s_cselect_b32 s30, s18, s13
	s_add_i32 s72, s50, s3
	ds_read_b128 v[130:133], v217
	ds_read_b128 v[134:137], v217 offset:1024
	ds_read_b128 v[138:141], v217 offset:2048
	ds_read_b128 v[142:145], v217 offset:3072
	ds_read_b128 v[146:149], v218
	ds_read_b128 v[150:153], v218 offset:1024
	ds_read_b128 v[154:157], v218 offset:2048
	ds_read_b128 v[158:161], v218 offset:3072
	s_add_i32 m0, s37, 0xc000
	s_add_i32 s71, s37, 0xe000
	s_add_i32 s73, s72, 0x2000
	s_add_u32 s48, s30, 0x40000
	s_addc_u32 s49, s31, 0
	s_add_i32 s74, s51, s3
	s_add_i32 s75, s74, 0x2000
	s_add_i32 s76, 0, 0x18000
	s_add_i32 s77, 0, 0x1c000
	s_add_u32 s26, s28, 0x40000
	s_addc_u32 s27, s29, 0
	s_add_i32 s68, s76, s3
	s_add_i32 s21, s68, 0x2000
	s_add_u32 s24, s30, 0x40080
	s_addc_u32 s25, s31, 0
	s_add_i32 s70, s77, s3
	s_add_i32 s69, s70, 0x2000
	s_cmp_lg_u32 s65, 12
	ds_read_b128 v[162:165], v219
	ds_read_b128 v[166:169], v219 offset:1024
	ds_read_b128 v[170:173], v219 offset:2048
	ds_read_b128 v[174:177], v219 offset:3072
	ds_read_b128 v[178:181], v219 offset:4096
	ds_read_b128 v[182:185], v219 offset:5120
	ds_read_b128 v[186:189], v219 offset:6144
	ds_read_b128 v[190:193], v219 offset:7168
	global_load_lds_dwordx4 v206, s[22:23]
	s_mov_b32 m0, s71
	s_nop 0
	global_load_lds_dwordx4 v208, s[22:23]
	s_waitcnt vmcnt(16)
	s_waitcnt lgkmcnt(0)
	s_barrier
	s_setprio 1
	s_waitcnt lgkmcnt(0)
	v_mfma_f32_16x16x32_bf16 v[126:129], v[130:133], v[162:165], 0
	v_mfma_f32_16x16x32_bf16 v[118:121], v[138:141], v[162:165], 0
	v_mfma_f32_16x16x32_bf16 v[110:113], v[130:133], v[170:173], 0
	v_mfma_f32_16x16x32_bf16 v[102:105], v[138:141], v[170:173], 0
	v_mfma_f32_16x16x32_bf16 v[94:97], v[130:133], v[178:181], 0
	v_mfma_f32_16x16x32_bf16 v[86:89], v[138:141], v[178:181], 0
	v_mfma_f32_16x16x32_bf16 v[78:81], v[130:133], v[186:189], 0
	v_mfma_f32_16x16x32_bf16 v[70:73], v[138:141], v[186:189], 0
	v_mfma_f32_16x16x32_bf16 v[126:129], v[134:137], v[166:169], v[126:129]
	v_mfma_f32_16x16x32_bf16 v[118:121], v[142:145], v[166:169], v[118:121]
	v_mfma_f32_16x16x32_bf16 v[110:113], v[134:137], v[174:177], v[110:113]
	v_mfma_f32_16x16x32_bf16 v[102:105], v[142:145], v[174:177], v[102:105]
	v_mfma_f32_16x16x32_bf16 v[94:97], v[134:137], v[182:185], v[94:97]
	v_mfma_f32_16x16x32_bf16 v[86:89], v[142:145], v[182:185], v[86:89]
	v_mfma_f32_16x16x32_bf16 v[78:81], v[134:137], v[190:193], v[78:81]
	v_mfma_f32_16x16x32_bf16 v[70:73], v[142:145], v[190:193], v[70:73]
	s_setprio 0
	s_setprio 1
	v_mfma_f32_16x16x32_bf16 v[122:125], v[146:149], v[162:165], 0
	v_mfma_f32_16x16x32_bf16 v[114:117], v[154:157], v[162:165], 0
	v_mfma_f32_16x16x32_bf16 v[106:109], v[146:149], v[170:173], 0
	v_mfma_f32_16x16x32_bf16 v[98:101], v[154:157], v[170:173], 0
	v_mfma_f32_16x16x32_bf16 v[90:93], v[146:149], v[178:181], 0
	v_mfma_f32_16x16x32_bf16 v[82:85], v[154:157], v[178:181], 0
	v_mfma_f32_16x16x32_bf16 v[74:77], v[146:149], v[186:189], 0
	v_mfma_f32_16x16x32_bf16 v[66:69], v[154:157], v[186:189], 0
	v_mfma_f32_16x16x32_bf16 v[122:125], v[150:153], v[166:169], v[122:125]
	v_mfma_f32_16x16x32_bf16 v[114:117], v[158:161], v[166:169], v[114:117]
	v_mfma_f32_16x16x32_bf16 v[106:109], v[150:153], v[174:177], v[106:109]
	v_mfma_f32_16x16x32_bf16 v[98:101], v[158:161], v[174:177], v[98:101]
	v_mfma_f32_16x16x32_bf16 v[90:93], v[150:153], v[182:185], v[90:93]
	v_mfma_f32_16x16x32_bf16 v[82:85], v[158:161], v[182:185], v[82:85]
	v_mfma_f32_16x16x32_bf16 v[74:77], v[150:153], v[190:193], v[74:77]
	v_mfma_f32_16x16x32_bf16 v[66:69], v[158:161], v[190:193], v[66:69]
	s_setprio 0
	s_barrier
	s_mov_b32 m0, s72
	ds_read_b128 v[162:165], v219 offset:16384
	ds_read_b128 v[166:169], v219 offset:17408
	ds_read_b128 v[170:173], v219 offset:18432
	ds_read_b128 v[174:177], v219 offset:19456
	ds_read_b128 v[178:181], v219 offset:20480
	ds_read_b128 v[182:185], v219 offset:21504
	ds_read_b128 v[186:189], v219 offset:22528
	ds_read_b128 v[190:193], v219 offset:23552
	global_load_lds_dwordx4 v200, s[30:31]
	s_mov_b32 m0, s73
	s_nop 0
	global_load_lds_dwordx4 v196, s[30:31]
	s_mov_b32 m0, s74
	s_nop 0
	global_load_lds_dwordx4 v200, s[48:49]
	s_mov_b32 m0, s75
	s_nop 0
	global_load_lds_dwordx4 v196, s[48:49]
	s_mov_b32 m0, s37
	s_nop 0
	global_load_lds_dwordx4 v202, s[28:29]
	s_mov_b32 m0, s38
	s_nop 0
	global_load_lds_dwordx4 v198, s[28:29]
	s_waitcnt vmcnt(16)
	s_waitcnt lgkmcnt(0)
	s_barrier
; #define PG8_STAGE(bufoff, gbase, voff) do { _Pragma("unroll") for (int _i = 0; _i < 2; ++_i) \
;         __builtin_amdgcn_global_load_lds((const unsigned*)((const char*)(gbase) + (voff)[_i]), (LAS unsigned*)(lds + (bufoff) + ldsw + _i * 8192), 16, 0, 0); } while (0)
; #define PG8_LDA(dst, b, h) do { _Pragma("unroll") for (int m = 0; m < 4; ++m) _Pragma("unroll") for (int k = 0; k < 2; ++k) dst[m][k] = *(const LAS bf16x8*)(lds + PG8_SA(b, h) + aoff + m * 2048 + k * 1024); } while (0)
; #define PG8_MMA(ai, bj, At, Bt) do { __builtin_amdgcn_s_setprio(1); _Pragma("unroll") for (int m = 0; m < 4; ++m) _Pragma("unroll") for (int n = 0; n < 2; ++n) _Pragma("unroll") for (int k = 0; k < 2; ++k) \
;         acc[ai][bj][m][n] = __builtin_amdgcn_mfma_f32_16x16x32_bf16(Bt[n][k], At[m][k], acc[ai][bj][m][n], 0, 0, 0); __builtin_amdgcn_s_setprio(0); } while (0)
; #define PG8_WAIT_V(n) asm volatile("s_waitcnt vmcnt(" #n ")" ::: "memory")
; #define PG8_WAIT_L(n) asm volatile("s_waitcnt lgkmcnt(" #n ")" ::: "memory")
; #define PG8_BAR __builtin_amdgcn_s_barrier()
; #define PG8_SCHED __builtin_amdgcn_sched_barrier(0)
; template <class Epi, class Sched>
; __device__ __forceinline__ void gemm_phase(LAS unsigned char* lds, const int lda, const int ldb, const int K, const Sched& S, const Epi& E) {
;     ...
;             PG8_WAIT_V(8); PG8_WAIT_L(0); PG8_BAR; PG8_MMA(0, 0, At, B0); PG8_MMA(0, 1, At, B1); PG8_BAR; PG8_SCHED;
;             PG8_LDA(At, 0, 1); PG8_STAGE(PG8_SB(0, 0), b2, voffB); PG8_STAGE(PG8_SB(0, 1), b2 + hstepB, voffB); PG8_STAGE(PG8_SA(0, 0), a2, voffA);
;             PG8_WAIT_V(8); PG8_WAIT_L(0); PG8_BAR; PG8_MMA(1, 0, At, B0); PG8_MMA(1, 1, At, B1); PG8_BAR; PG8_SCHED;
	s_setprio 1
	s_waitcnt lgkmcnt(0)
	v_mfma_f32_16x16x32_bf16 v[62:65], v[130:133], v[162:165], 0
	v_mfma_f32_16x16x32_bf16 v[54:57], v[138:141], v[162:165], 0
	v_mfma_f32_16x16x32_bf16 v[46:49], v[130:133], v[170:173], 0
	v_mfma_f32_16x16x32_bf16 v[38:41], v[138:141], v[170:173], 0
	v_mfma_f32_16x16x32_bf16 v[30:33], v[130:133], v[178:181], 0
	v_mfma_f32_16x16x32_bf16 v[22:25], v[138:141], v[178:181], 0
	v_mfma_f32_16x16x32_bf16 v[14:17], v[130:133], v[186:189], 0
	v_mfma_f32_16x16x32_bf16 v[6:9], v[138:141], v[186:189], 0
	v_mfma_f32_16x16x32_bf16 v[62:65], v[134:137], v[166:169], v[62:65]
	v_mfma_f32_16x16x32_bf16 v[54:57], v[142:145], v[166:169], v[54:57]
	v_mfma_f32_16x16x32_bf16 v[46:49], v[134:137], v[174:177], v[46:49]
	v_mfma_f32_16x16x32_bf16 v[38:41], v[142:145], v[174:177], v[38:41]
	v_mfma_f32_16x16x32_bf16 v[30:33], v[134:137], v[182:185], v[30:33]
	v_mfma_f32_16x16x32_bf16 v[22:25], v[142:145], v[182:185], v[22:25]
	v_mfma_f32_16x16x32_bf16 v[14:17], v[134:137], v[190:193], v[14:17]
	v_mfma_f32_16x16x32_bf16 v[6:9], v[142:145], v[190:193], v[6:9]
	s_setprio 0
	s_setprio 1
	v_mfma_f32_16x16x32_bf16 v[58:61], v[146:149], v[162:165], 0
	v_mfma_f32_16x16x32_bf16 v[50:53], v[154:157], v[162:165], 0
	v_mfma_f32_16x16x32_bf16 v[42:45], v[146:149], v[170:173], 0
	v_mfma_f32_16x16x32_bf16 v[34:37], v[154:157], v[170:173], 0
	v_mfma_f32_16x16x32_bf16 v[26:29], v[146:149], v[178:181], 0
	v_mfma_f32_16x16x32_bf16 v[18:21], v[154:157], v[178:181], 0
	v_mfma_f32_16x16x32_bf16 v[10:13], v[146:149], v[186:189], 0
	v_mfma_f32_16x16x32_bf16 v[2:5], v[154:157], v[186:189], 0
	v_mfma_f32_16x16x32_bf16 v[58:61], v[150:153], v[166:169], v[58:61]
	v_mfma_f32_16x16x32_bf16 v[50:53], v[158:161], v[166:169], v[50:53]
	v_mfma_f32_16x16x32_bf16 v[42:45], v[150:153], v[174:177], v[42:45]
	v_mfma_f32_16x16x32_bf16 v[34:37], v[158:161], v[174:177], v[34:37]
	v_mfma_f32_16x16x32_bf16 v[26:29], v[150:153], v[182:185], v[26:29]
	v_mfma_f32_16x16x32_bf16 v[18:21], v[158:161], v[182:185], v[18:21]
	v_mfma_f32_16x16x32_bf16 v[10:13], v[150:153], v[190:193], v[10:13]
	v_mfma_f32_16x16x32_bf16 v[2:5], v[158:161], v[190:193], v[2:5]
	s_setprio 0
	s_barrier
	s_branch .Lpeel1_join
; #define PG8_STAGE(bufoff, gbase, voff) do { _Pragma("unroll") for (int _i = 0; _i < 2; ++_i) \
;         __builtin_amdgcn_global_load_lds((const unsigned*)((const char*)(gbase) + (voff)[_i]), (LAS unsigned*)(lds + (bufoff) + ldsw + _i * 8192), 16, 0, 0); } while (0)
; #define PG8_LDA(dst, b, h) do { _Pragma("unroll") for (int m = 0; m < 4; ++m) _Pragma("unroll") for (int k = 0; k < 2; ++k) dst[m][k] = *(const LAS bf16x8*)(lds + PG8_SA(b, h) + aoff + m * 2048 + k * 1024); } while (0)
; #define PG8_LDB(dst, b, h) do { _Pragma("unroll") for (int n = 0; n < 2; ++n) _Pragma("unroll") for (int k = 0; k < 2; ++k) dst[n][k] = *(const LAS bf16x8*)(lds + PG8_SB(b, h) + boff + n * 2048 + k * 1024); } while (0)
; #define PG8_MMA(ai, bj, At, Bt) do { __builtin_amdgcn_s_setprio(1); _Pragma("unroll") for (int m = 0; m < 4; ++m) _Pragma("unroll") for (int n = 0; n < 2; ++n) _Pragma("unroll") for (int k = 0; k < 2; ++k) \
;         acc[ai][bj][m][n] = __builtin_amdgcn_mfma_f32_16x16x32_bf16(Bt[n][k], At[m][k], acc[ai][bj][m][n], 0, 0, 0); __builtin_amdgcn_s_setprio(0); } while (0)
; #define PG8_WAIT_V(n) asm volatile("s_waitcnt vmcnt(" #n ")" ::: "memory")
; template <class Epi, class Sched>
; __device__ __forceinline__ void gemm_phase(LAS unsigned char* lds, const int lda, const int ldb, const int K, const Sched& S, const Epi& E) {
;     ...
;         const bool has_next = S.next(ui + 1, nxt);
;         const char* nA = has_next ? nxt.A : cA; const char* nB = has_next ? nxt.B : cB;
;         for (int t = 0; t < nt; t += 2) {
;             const bool last = (t == nt - 2);
;             const char* a1 = cA + (size_t)(t + 1) * kstep;
;             const char* a2 = last ? nA : cA + (size_t)(t + 2) * kstep; const char* b2 = last ? nB : cB + (size_t)(t + 2) * kstep;
;             const char* a3 = a2 + kstep; const char* b3 = b2 + kstep;
;             PG8_LDB(B0, 0, 0); PG8_LDB(B1, 0, 1); PG8_SCHED; PG8_LDA(At, 0, 0); PG8_STAGE(PG8_SA(1, 1), a1 + hstepA, voffA);
;             PG8_WAIT_V(8); PG8_WAIT_L(0); PG8_BAR; PG8_MMA(0, 0, At, B0); PG8_MMA(0, 1, At, B1); PG8_BAR; PG8_SCHED;
;             PG8_LDA(At, 0, 1); PG8_STAGE(PG8_SB(0, 0), b2, voffB); PG8_STAGE(PG8_SB(0, 1), b2 + hstepB, voffB); PG8_STAGE(PG8_SA(0, 0), a2, voffA);
;             PG8_WAIT_V(8); PG8_WAIT_L(0); PG8_BAR; PG8_MMA(1, 0, At, B0); PG8_MMA(1, 1, At, B1); PG8_BAR; PG8_SCHED;
.Lpeel1_first:
	s_add_u32 s21, s22, 0xfffc0080
	s_addc_u32 s24, s23, -1
	s_cmp_eq_u32 s65, 12
	s_cselect_b32 s29, s17, s24
	s_cselect_b32 s28, s16, s21
	s_cselect_b32 s31, s19, s15
	s_cselect_b32 s30, s18, s13
	s_add_i32 s72, s50, s3
	ds_read_b128 v[130:133], v217
	ds_read_b128 v[134:137], v217 offset:1024
	ds_read_b128 v[138:141], v217 offset:2048
	ds_read_b128 v[142:145], v217 offset:3072
	ds_read_b128 v[146:149], v218
	ds_read_b128 v[150:153], v218 offset:1024
	ds_read_b128 v[154:157], v218 offset:2048
	ds_read_b128 v[158:161], v218 offset:3072
	s_add_i32 m0, s37, 0xc000
	s_add_i32 s71, s37, 0xe000
	s_add_i32 s73, s72, 0x2000
	s_add_u32 s48, s30, 0x40000
	s_addc_u32 s49, s31, 0
	s_add_i32 s74, s51, s3
	s_add_i32 s75, s74, 0x2000
	s_add_i32 s76, 0, 0x18000
	s_add_i32 s77, 0, 0x1c000
	s_add_u32 s26, s28, 0x40000
	s_addc_u32 s27, s29, 0
	s_add_i32 s68, s76, s3
	s_add_i32 s21, s68, 0x2000
	s_add_u32 s24, s30, 0x40080
	s_addc_u32 s25, s31, 0
	s_add_i32 s70, s77, s3
	s_add_i32 s69, s70, 0x2000
	s_cmp_lg_u32 s65, 12
	ds_read_b128 v[162:165], v219
	ds_read_b128 v[166:169], v219 offset:1024
	ds_read_b128 v[170:173], v219 offset:2048
	ds_read_b128 v[174:177], v219 offset:3072
	ds_read_b128 v[178:181], v219 offset:4096
	ds_read_b128 v[182:185], v219 offset:5120
	ds_read_b128 v[186:189], v219 offset:6144
	ds_read_b128 v[190:193], v219 offset:7168
	global_load_lds_dwordx4 v206, s[22:23]
	s_mov_b32 m0, s71
	s_nop 0
	global_load_lds_dwordx4 v208, s[22:23]
	s_waitcnt vmcnt(8)
	s_waitcnt lgkmcnt(0)
	s_barrier
	s_setprio 1
	s_waitcnt lgkmcnt(0)
	v_mfma_f32_16x16x32_bf16 v[126:129], v[130:133], v[162:165], 0
	v_mfma_f32_16x16x32_bf16 v[118:121], v[138:141], v[162:165], 0
	v_mfma_f32_16x16x32_bf16 v[110:113], v[130:133], v[170:173], 0
	v_mfma_f32_16x16x32_bf16 v[102:105], v[138:141], v[170:173], 0
	v_mfma_f32_16x16x32_bf16 v[94:97], v[130:133], v[178:181], 0
	v_mfma_f32_16x16x32_bf16 v[86:89], v[138:141], v[178:181], 0
	v_mfma_f32_16x16x32_bf16 v[78:81], v[130:133], v[186:189], 0
	v_mfma_f32_16x16x32_bf16 v[70:73], v[138:141], v[186:189], 0
	v_mfma_f32_16x16x32_bf16 v[126:129], v[134:137], v[166:169], v[126:129]
	v_mfma_f32_16x16x32_bf16 v[118:121], v[142:145], v[166:169], v[118:121]
	v_mfma_f32_16x16x32_bf16 v[110:113], v[134:137], v[174:177], v[110:113]
	v_mfma_f32_16x16x32_bf16 v[102:105], v[142:145], v[174:177], v[102:105]
	v_mfma_f32_16x16x32_bf16 v[94:97], v[134:137], v[182:185], v[94:97]
	v_mfma_f32_16x16x32_bf16 v[86:89], v[142:145], v[182:185], v[86:89]
	v_mfma_f32_16x16x32_bf16 v[78:81], v[134:137], v[190:193], v[78:81]
	v_mfma_f32_16x16x32_bf16 v[70:73], v[142:145], v[190:193], v[70:73]
	s_setprio 0
	s_setprio 1
	v_mfma_f32_16x16x32_bf16 v[122:125], v[146:149], v[162:165], 0
	v_mfma_f32_16x16x32_bf16 v[114:117], v[154:157], v[162:165], 0
	v_mfma_f32_16x16x32_bf16 v[106:109], v[146:149], v[170:173], 0
	v_mfma_f32_16x16x32_bf16 v[98:101], v[154:157], v[170:173], 0
	v_mfma_f32_16x16x32_bf16 v[90:93], v[146:149], v[178:181], 0
	v_mfma_f32_16x16x32_bf16 v[82:85], v[154:157], v[178:181], 0
	v_mfma_f32_16x16x32_bf16 v[74:77], v[146:149], v[186:189], 0
	v_mfma_f32_16x16x32_bf16 v[66:69], v[154:157], v[186:189], 0
	v_mfma_f32_16x16x32_bf16 v[122:125], v[150:153], v[166:169], v[122:125]
	v_mfma_f32_16x16x32_bf16 v[114:117], v[158:161], v[166:169], v[114:117]
	v_mfma_f32_16x16x32_bf16 v[106:109], v[150:153], v[174:177], v[106:109]
	v_mfma_f32_16x16x32_bf16 v[98:101], v[158:161], v[174:177], v[98:101]
	v_mfma_f32_16x16x32_bf16 v[90:93], v[150:153], v[182:185], v[90:93]
	v_mfma_f32_16x16x32_bf16 v[82:85], v[158:161], v[182:185], v[82:85]
	v_mfma_f32_16x16x32_bf16 v[74:77], v[150:153], v[190:193], v[74:77]
	v_mfma_f32_16x16x32_bf16 v[66:69], v[158:161], v[190:193], v[66:69]
	s_setprio 0
	s_barrier
	s_mov_b32 m0, s72
	ds_read_b128 v[162:165], v219 offset:16384
	ds_read_b128 v[166:169], v219 offset:17408
	ds_read_b128 v[170:173], v219 offset:18432
	ds_read_b128 v[174:177], v219 offset:19456
	ds_read_b128 v[178:181], v219 offset:20480
	ds_read_b128 v[182:185], v219 offset:21504
	ds_read_b128 v[186:189], v219 offset:22528
	ds_read_b128 v[190:193], v219 offset:23552
	global_load_lds_dwordx4 v200, s[30:31]
	s_mov_b32 m0, s73
	s_nop 0
	global_load_lds_dwordx4 v196, s[30:31]
	s_mov_b32 m0, s74
	s_nop 0
	global_load_lds_dwordx4 v200, s[48:49]
	s_mov_b32 m0, s75
	s_nop 0
	global_load_lds_dwordx4 v196, s[48:49]
	s_mov_b32 m0, s37
	s_nop 0
	global_load_lds_dwordx4 v202, s[28:29]
	s_mov_b32 m0, s38
	s_nop 0
	global_load_lds_dwordx4 v198, s[28:29]
	s_waitcnt vmcnt(8)
	s_waitcnt lgkmcnt(0)
	s_barrier
	s_setprio 1
	s_waitcnt lgkmcnt(0)
	v_mfma_f32_16x16x32_bf16 v[62:65], v[130:133], v[162:165], 0
	v_mfma_f32_16x16x32_bf16 v[54:57], v[138:141], v[162:165], 0
	v_mfma_f32_16x16x32_bf16 v[46:49], v[130:133], v[170:173], 0
	v_mfma_f32_16x16x32_bf16 v[38:41], v[138:141], v[170:173], 0
	v_mfma_f32_16x16x32_bf16 v[30:33], v[130:133], v[178:181], 0
	v_mfma_f32_16x16x32_bf16 v[22:25], v[138:141], v[178:181], 0
	v_mfma_f32_16x16x32_bf16 v[14:17], v[130:133], v[186:189], 0
	v_mfma_f32_16x16x32_bf16 v[6:9], v[138:141], v[186:189], 0
	v_mfma_f32_16x16x32_bf16 v[62:65], v[134:137], v[166:169], v[62:65]
	v_mfma_f32_16x16x32_bf16 v[54:57], v[142:145], v[166:169], v[54:57]
	v_mfma_f32_16x16x32_bf16 v[46:49], v[134:137], v[174:177], v[46:49]
	v_mfma_f32_16x16x32_bf16 v[38:41], v[142:145], v[174:177], v[38:41]
	v_mfma_f32_16x16x32_bf16 v[30:33], v[134:137], v[182:185], v[30:33]
	v_mfma_f32_16x16x32_bf16 v[22:25], v[142:145], v[182:185], v[22:25]
	v_mfma_f32_16x16x32_bf16 v[14:17], v[134:137], v[190:193], v[14:17]
	v_mfma_f32_16x16x32_bf16 v[6:9], v[142:145], v[190:193], v[6:9]
	s_setprio 0
	s_setprio 1
	v_mfma_f32_16x16x32_bf16 v[58:61], v[146:149], v[162:165], 0
	v_mfma_f32_16x16x32_bf16 v[50:53], v[154:157], v[162:165], 0
	v_mfma_f32_16x16x32_bf16 v[42:45], v[146:149], v[170:173], 0
	v_mfma_f32_16x16x32_bf16 v[34:37], v[154:157], v[170:173], 0
	v_mfma_f32_16x16x32_bf16 v[26:29], v[146:149], v[178:181], 0
	v_mfma_f32_16x16x32_bf16 v[18:21], v[154:157], v[178:181], 0
	v_mfma_f32_16x16x32_bf16 v[10:13], v[146:149], v[186:189], 0
	v_mfma_f32_16x16x32_bf16 v[2:5], v[154:157], v[186:189], 0
	v_mfma_f32_16x16x32_bf16 v[58:61], v[150:153], v[166:169], v[58:61]
	v_mfma_f32_16x16x32_bf16 v[50:53], v[158:161], v[166:169], v[50:53]
	v_mfma_f32_16x16x32_bf16 v[42:45], v[150:153], v[174:177], v[42:45]
	v_mfma_f32_16x16x32_bf16 v[34:37], v[158:161], v[174:177], v[34:37]
	v_mfma_f32_16x16x32_bf16 v[26:29], v[150:153], v[182:185], v[26:29]
	v_mfma_f32_16x16x32_bf16 v[18:21], v[158:161], v[182:185], v[18:21]
	v_mfma_f32_16x16x32_bf16 v[10:13], v[150:153], v[190:193], v[10:13]
	v_mfma_f32_16x16x32_bf16 v[2:5], v[158:161], v[190:193], v[2:5]
	s_setprio 0
	s_barrier
	s_branch .Lpeel1_join

; #define PG8_STAGE(bufoff, gbase, voff) do { _Pragma("unroll") for (int _i = 0; _i < 2; ++_i) \
;         __builtin_amdgcn_global_load_lds((const unsigned*)((const char*)(gbase) + (voff)[_i]), (LAS unsigned*)(lds + (bufoff) + ldsw + _i * 8192), 16, 0, 0); } while (0)
; #define PG8_LDA(dst, b, h) do { _Pragma("unroll") for (int m = 0; m < 4; ++m) _Pragma("unroll") for (int k = 0; k < 2; ++k) dst[m][k] = *(const LAS bf16x8*)(lds + PG8_SA(b, h) + aoff + m * 2048 + k * 1024); } while (0)
; #define PG8_LDB(dst, b, h) do { _Pragma("unroll") for (int n = 0; n < 2; ++n) _Pragma("unroll") for (int k = 0; k < 2; ++k) dst[n][k] = *(const LAS bf16x8*)(lds + PG8_SB(b, h) + boff + n * 2048 + k * 1024); } while (0)
; #define PG8_MMA(ai, bj, At, Bt) do { __builtin_amdgcn_s_setprio(1); _Pragma("unroll") for (int m = 0; m < 4; ++m) _Pragma("unroll") for (int n = 0; n < 2; ++n) _Pragma("unroll") for (int k = 0; k < 2; ++k) \
;         acc[ai][bj][m][n] = __builtin_amdgcn_mfma_f32_16x16x32_bf16(Bt[n][k], At[m][k], acc[ai][bj][m][n], 0, 0, 0); __builtin_amdgcn_s_setprio(0); } while (0)
; #define PG8_WAIT_V(n) asm volatile("s_waitcnt vmcnt(" #n ")" ::: "memory")
; template <class Epi, class Sched>
; __device__ __forceinline__ void gemm_phase(LAS unsigned char* lds, const int lda, const int ldb, const int K, const Sched& S, const Epi& E) {
;     ...
;         const bool has_next = S.next(ui + 1, nxt);
;         const char* nA = has_next ? nxt.A : cA; const char* nB = has_next ? nxt.B : cB;
;         for (int t = 0; t < nt; t += 2) {
;             const bool last = (t == nt - 2);
;             const char* a1 = cA + (size_t)(t + 1) * kstep;
;             const char* a2 = last ? nA : cA + (size_t)(t + 2) * kstep; const char* b2 = last ? nB : cB + (size_t)(t + 2) * kstep;
;             const char* a3 = a2 + kstep; const char* b3 = b2 + kstep;
;             PG8_LDB(B0, 0, 0); PG8_LDB(B1, 0, 1); PG8_SCHED; PG8_LDA(At, 0, 0); PG8_STAGE(PG8_SA(1, 1), a1 + hstepA, voffA);
;             PG8_WAIT_V(8); PG8_WAIT_L(0); PG8_BAR; PG8_MMA(0, 0, At, B0); PG8_MMA(0, 1, At, B1); PG8_BAR; PG8_SCHED;
;             PG8_LDA(At, 0, 1); PG8_STAGE(PG8_SB(0, 0), b2, voffB); PG8_STAGE(PG8_SB(0, 1), b2 + hstepB, voffB); PG8_STAGE(PG8_SA(0, 0), a2, voffA);
;             PG8_WAIT_V(8); PG8_WAIT_L(0); PG8_BAR; PG8_MMA(1, 0, At, B0); PG8_MMA(1, 1, At, B1); PG8_BAR; PG8_SCHED;
.LBB0_424:
	s_lshl_b32 s4, s4, 8
	s_ashr_i32 s5, s4, 31
	s_add_u32 s6, s6, 0x40080
	s_addc_u32 s7, s7, 0
	v_lshl_add_u64 v[220:221], s[4:5], 2, v[206:207]
	s_add_u32 s5, s8, 0x100
	s_addc_u32 s51, s9, 0
	s_mov_b32 s69, -2
	v_add_u32_e32 v234, 0x80, v202
	v_add_u32_e32 v235, 0x80, v198
	v_add_u32_e32 v236, 0x80, v204
	v_add_u32_e32 v237, 0x80, v200
	s_cmp_eq_u32 s77, 1
	s_cbranch_scc1 .Lpeel3_first
	s_add_u32 s8, s6, 0xfffc0080
	s_addc_u32 s9, s7, -1
	s_cmp_eq_u32 s69, 12
	s_cselect_b32 s13, s71, s9
	s_cselect_b32 s12, s70, s8
	s_cselect_b32 s15, s73, s51
	s_cselect_b32 s14, s72, s5
	s_add_i32 s81, s63, s36
	ds_read_b128 v[130:133], v222
	ds_read_b128 v[134:137], v222 offset:1024
	ds_read_b128 v[138:141], v222 offset:2048
	ds_read_b128 v[142:145], v222 offset:3072
	ds_read_b128 v[146:149], v223
	ds_read_b128 v[150:153], v223 offset:1024
	ds_read_b128 v[154:157], v223 offset:2048
	ds_read_b128 v[158:161], v223 offset:3072
	s_add_i32 m0, s39, 0xc000
	s_add_i32 s80, s39, 0xe000
	s_add_i32 s82, s81, 0x2000
	s_add_u32 s16, s14, 0x40000
	s_addc_u32 s17, s15, 0
	s_add_i32 s83, s64, s36
	s_add_i32 s84, s83, 0x2000
	s_add_i32 s85, 0, 0x18000
	s_add_i32 s86, 0, 0x1c000
	s_add_u32 s10, s12, 0x40000
	s_addc_u32 s11, s13, 0
	s_add_i32 s75, s85, s36
	s_add_i32 s74, s75, 0x2000
	s_add_u32 s8, s14, 0x40080
	s_addc_u32 s9, s15, 0
	s_add_i32 s79, s86, s36
	s_add_i32 s78, s79, 0x2000
	s_cmp_lg_u32 s69, 12
	ds_read_b128 v[162:165], v224
	ds_read_b128 v[166:169], v224 offset:1024
	ds_read_b128 v[170:173], v224 offset:2048
	ds_read_b128 v[174:177], v224 offset:3072
	ds_read_b128 v[178:181], v224 offset:4096
	ds_read_b128 v[182:185], v224 offset:5120
	ds_read_b128 v[186:189], v224 offset:6144
	ds_read_b128 v[190:193], v224 offset:7168
	global_load_lds_dwordx4 v212, s[6:7]
	s_mov_b32 m0, s80
	s_nop 0
	global_load_lds_dwordx4 v214, s[6:7]
	s_waitcnt vmcnt(24)
	s_waitcnt lgkmcnt(0)
	s_barrier
	s_setprio 1
	s_waitcnt lgkmcnt(0)
	v_mfma_f32_16x16x32_bf16 v[126:129], v[130:133], v[162:165], 0
	v_mfma_f32_16x16x32_bf16 v[118:121], v[138:141], v[162:165], 0
	v_mfma_f32_16x16x32_bf16 v[110:113], v[130:133], v[170:173], 0
	v_mfma_f32_16x16x32_bf16 v[102:105], v[138:141], v[170:173], 0
	v_mfma_f32_16x16x32_bf16 v[94:97], v[130:133], v[178:181], 0
	v_mfma_f32_16x16x32_bf16 v[86:89], v[138:141], v[178:181], 0
	v_mfma_f32_16x16x32_bf16 v[78:81], v[130:133], v[186:189], 0
	v_mfma_f32_16x16x32_bf16 v[70:73], v[138:141], v[186:189], 0
	v_mfma_f32_16x16x32_bf16 v[126:129], v[134:137], v[166:169], v[126:129]
	v_mfma_f32_16x16x32_bf16 v[118:121], v[142:145], v[166:169], v[118:121]
	v_mfma_f32_16x16x32_bf16 v[110:113], v[134:137], v[174:177], v[110:113]
	v_mfma_f32_16x16x32_bf16 v[102:105], v[142:145], v[174:177], v[102:105]
	v_mfma_f32_16x16x32_bf16 v[94:97], v[134:137], v[182:185], v[94:97]
	v_mfma_f32_16x16x32_bf16 v[86:89], v[142:145], v[182:185], v[86:89]
	v_mfma_f32_16x16x32_bf16 v[78:81], v[134:137], v[190:193], v[78:81]
	v_mfma_f32_16x16x32_bf16 v[70:73], v[142:145], v[190:193], v[70:73]
	s_setprio 0
	s_setprio 1
	v_mfma_f32_16x16x32_bf16 v[122:125], v[146:149], v[162:165], 0
	v_mfma_f32_16x16x32_bf16 v[114:117], v[154:157], v[162:165], 0
	v_mfma_f32_16x16x32_bf16 v[106:109], v[146:149], v[170:173], 0
	v_mfma_f32_16x16x32_bf16 v[98:101], v[154:157], v[170:173], 0
	v_mfma_f32_16x16x32_bf16 v[90:93], v[146:149], v[178:181], 0
	v_mfma_f32_16x16x32_bf16 v[82:85], v[154:157], v[178:181], 0
	v_mfma_f32_16x16x32_bf16 v[74:77], v[146:149], v[186:189], 0
	v_mfma_f32_16x16x32_bf16 v[66:69], v[154:157], v[186:189], 0
	v_mfma_f32_16x16x32_bf16 v[122:125], v[150:153], v[166:169], v[122:125]
	v_mfma_f32_16x16x32_bf16 v[114:117], v[158:161], v[166:169], v[114:117]
	v_mfma_f32_16x16x32_bf16 v[106:109], v[150:153], v[174:177], v[106:109]
	v_mfma_f32_16x16x32_bf16 v[98:101], v[158:161], v[174:177], v[98:101]
	v_mfma_f32_16x16x32_bf16 v[90:93], v[150:153], v[182:185], v[90:93]
	v_mfma_f32_16x16x32_bf16 v[82:85], v[158:161], v[182:185], v[82:85]
	v_mfma_f32_16x16x32_bf16 v[74:77], v[150:153], v[190:193], v[74:77]
	v_mfma_f32_16x16x32_bf16 v[66:69], v[158:161], v[190:193], v[66:69]
	s_setprio 0
	s_barrier
	s_mov_b32 m0, s81
	ds_read_b128 v[162:165], v224 offset:16384
	ds_read_b128 v[166:169], v224 offset:17408
	ds_read_b128 v[170:173], v224 offset:18432
	ds_read_b128 v[174:177], v224 offset:19456
	ds_read_b128 v[178:181], v224 offset:20480
	ds_read_b128 v[182:185], v224 offset:21504
	ds_read_b128 v[186:189], v224 offset:22528
	ds_read_b128 v[190:193], v224 offset:23552
	global_load_lds_dwordx4 v202, s[14:15]
	s_mov_b32 m0, s82
	s_nop 0
	global_load_lds_dwordx4 v198, s[14:15]
	s_mov_b32 m0, s83
	s_nop 0
	global_load_lds_dwordx4 v202, s[16:17]
	s_mov_b32 m0, s84
	s_nop 0
	global_load_lds_dwordx4 v198, s[16:17]
	s_mov_b32 m0, s39
	s_nop 0
	global_load_lds_dwordx4 v204, s[12:13]
	s_mov_b32 m0, s40
	s_nop 0
	global_load_lds_dwordx4 v200, s[12:13]
	s_waitcnt vmcnt(24)
	s_waitcnt lgkmcnt(0)
	s_barrier
; #define PG8_STAGE(bufoff, gbase, voff) do { _Pragma("unroll") for (int _i = 0; _i < 2; ++_i) \
;         __builtin_amdgcn_global_load_lds((const unsigned*)((const char*)(gbase) + (voff)[_i]), (LAS unsigned*)(lds + (bufoff) + ldsw + _i * 8192), 16, 0, 0); } while (0)
; #define PG8_LDA(dst, b, h) do { _Pragma("unroll") for (int m = 0; m < 4; ++m) _Pragma("unroll") for (int k = 0; k < 2; ++k) dst[m][k] = *(const LAS bf16x8*)(lds + PG8_SA(b, h) + aoff + m * 2048 + k * 1024); } while (0)
; #define PG8_MMA(ai, bj, At, Bt) do { __builtin_amdgcn_s_setprio(1); _Pragma("unroll") for (int m = 0; m < 4; ++m) _Pragma("unroll") for (int n = 0; n < 2; ++n) _Pragma("unroll") for (int k = 0; k < 2; ++k) \
;         acc[ai][bj][m][n] = __builtin_amdgcn_mfma_f32_16x16x32_bf16(Bt[n][k], At[m][k], acc[ai][bj][m][n], 0, 0, 0); __builtin_amdgcn_s_setprio(0); } while (0)
; #define PG8_WAIT_V(n) asm volatile("s_waitcnt vmcnt(" #n ")" ::: "memory")
; #define PG8_WAIT_L(n) asm volatile("s_waitcnt lgkmcnt(" #n ")" ::: "memory")
; #define PG8_BAR __builtin_amdgcn_s_barrier()
; #define PG8_SCHED __builtin_amdgcn_sched_barrier(0)
; template <class Epi, class Sched>
; __device__ __forceinline__ void gemm_phase(LAS unsigned char* lds, const int lda, const int ldb, const int K, const Sched& S, const Epi& E) {
;     ...
;             PG8_WAIT_V(8); PG8_WAIT_L(0); PG8_BAR; PG8_MMA(0, 0, At, B0); PG8_MMA(0, 1, At, B1); PG8_BAR; PG8_SCHED;
;             PG8_LDA(At, 0, 1); PG8_STAGE(PG8_SB(0, 0), b2, voffB); PG8_STAGE(PG8_SB(0, 1), b2 + hstepB, voffB); PG8_STAGE(PG8_SA(0, 0), a2, voffA);
;             PG8_WAIT_V(8); PG8_WAIT_L(0); PG8_BAR; PG8_MMA(1, 0, At, B0); PG8_MMA(1, 1, At, B1); PG8_BAR; PG8_SCHED;
	s_setprio 1
	s_waitcnt lgkmcnt(0)
	v_mfma_f32_16x16x32_bf16 v[62:65], v[130:133], v[162:165], 0
	v_mfma_f32_16x16x32_bf16 v[54:57], v[138:141], v[162:165], 0
	v_mfma_f32_16x16x32_bf16 v[46:49], v[130:133], v[170:173], 0
	v_mfma_f32_16x16x32_bf16 v[38:41], v[138:141], v[170:173], 0
	v_mfma_f32_16x16x32_bf16 v[30:33], v[130:133], v[178:181], 0
	v_mfma_f32_16x16x32_bf16 v[22:25], v[138:141], v[178:181], 0
	v_mfma_f32_16x16x32_bf16 v[14:17], v[130:133], v[186:189], 0
	v_mfma_f32_16x16x32_bf16 v[6:9], v[138:141], v[186:189], 0
	v_mfma_f32_16x16x32_bf16 v[62:65], v[134:137], v[166:169], v[62:65]
	v_mfma_f32_16x16x32_bf16 v[54:57], v[142:145], v[166:169], v[54:57]
	v_mfma_f32_16x16x32_bf16 v[46:49], v[134:137], v[174:177], v[46:49]
	v_mfma_f32_16x16x32_bf16 v[38:41], v[142:145], v[174:177], v[38:41]
	v_mfma_f32_16x16x32_bf16 v[30:33], v[134:137], v[182:185], v[30:33]
	v_mfma_f32_16x16x32_bf16 v[22:25], v[142:145], v[182:185], v[22:25]
	v_mfma_f32_16x16x32_bf16 v[14:17], v[134:137], v[190:193], v[14:17]
	v_mfma_f32_16x16x32_bf16 v[6:9], v[142:145], v[190:193], v[6:9]
	s_setprio 0
	s_setprio 1
	v_mfma_f32_16x16x32_bf16 v[58:61], v[146:149], v[162:165], 0
	v_mfma_f32_16x16x32_bf16 v[50:53], v[154:157], v[162:165], 0
	v_mfma_f32_16x16x32_bf16 v[42:45], v[146:149], v[170:173], 0
	v_mfma_f32_16x16x32_bf16 v[34:37], v[154:157], v[170:173], 0
	v_mfma_f32_16x16x32_bf16 v[26:29], v[146:149], v[178:181], 0
	v_mfma_f32_16x16x32_bf16 v[18:21], v[154:157], v[178:181], 0
	v_mfma_f32_16x16x32_bf16 v[10:13], v[146:149], v[186:189], 0
	v_mfma_f32_16x16x32_bf16 v[2:5], v[154:157], v[186:189], 0
	v_mfma_f32_16x16x32_bf16 v[58:61], v[150:153], v[166:169], v[58:61]
	v_mfma_f32_16x16x32_bf16 v[50:53], v[158:161], v[166:169], v[50:53]
	v_mfma_f32_16x16x32_bf16 v[42:45], v[150:153], v[174:177], v[42:45]
	v_mfma_f32_16x16x32_bf16 v[34:37], v[158:161], v[174:177], v[34:37]
	v_mfma_f32_16x16x32_bf16 v[26:29], v[150:153], v[182:185], v[26:29]
	v_mfma_f32_16x16x32_bf16 v[18:21], v[158:161], v[182:185], v[18:21]
	v_mfma_f32_16x16x32_bf16 v[10:13], v[150:153], v[190:193], v[10:13]
	v_mfma_f32_16x16x32_bf16 v[2:5], v[158:161], v[190:193], v[2:5]
	s_setprio 0
	s_barrier
	s_branch .Lpeel3_join
; #define PG8_STAGE(bufoff, gbase, voff) do { _Pragma("unroll") for (int _i = 0; _i < 2; ++_i) \
;         __builtin_amdgcn_global_load_lds((const unsigned*)((const char*)(gbase) + (voff)[_i]), (LAS unsigned*)(lds + (bufoff) + ldsw + _i * 8192), 16, 0, 0); } while (0)
; #define PG8_LDA(dst, b, h) do { _Pragma("unroll") for (int m = 0; m < 4; ++m) _Pragma("unroll") for (int k = 0; k < 2; ++k) dst[m][k] = *(const LAS bf16x8*)(lds + PG8_SA(b, h) + aoff + m * 2048 + k * 1024); } while (0)
; #define PG8_LDB(dst, b, h) do { _Pragma("unroll") for (int n = 0; n < 2; ++n) _Pragma("unroll") for (int k = 0; k < 2; ++k) dst[n][k] = *(const LAS bf16x8*)(lds + PG8_SB(b, h) + boff + n * 2048 + k * 1024); } while (0)
; #define PG8_MMA(ai, bj, At, Bt) do { __builtin_amdgcn_s_setprio(1); _Pragma("unroll") for (int m = 0; m < 4; ++m) _Pragma("unroll") for (int n = 0; n < 2; ++n) _Pragma("unroll") for (int k = 0; k < 2; ++k) \
;         acc[ai][bj][m][n] = __builtin_amdgcn_mfma_f32_16x16x32_bf16(Bt[n][k], At[m][k], acc[ai][bj][m][n], 0, 0, 0); __builtin_amdgcn_s_setprio(0); } while (0)
; #define PG8_WAIT_V(n) asm volatile("s_waitcnt vmcnt(" #n ")" ::: "memory")
; template <class Epi, class Sched>
; __device__ __forceinline__ void gemm_phase(LAS unsigned char* lds, const int lda, const int ldb, const int K, const Sched& S, const Epi& E) {
;     ...
;         const bool has_next = S.next(ui + 1, nxt);
;         const char* nA = has_next ? nxt.A : cA; const char* nB = has_next ? nxt.B : cB;
;         for (int t = 0; t < nt; t += 2) {
;             const bool last = (t == nt - 2);
;             const char* a1 = cA + (size_t)(t + 1) * kstep;
;             const char* a2 = last ? nA : cA + (size_t)(t + 2) * kstep; const char* b2 = last ? nB : cB + (size_t)(t + 2) * kstep;
;             const char* a3 = a2 + kstep; const char* b3 = b2 + kstep;
;             PG8_LDB(B0, 0, 0); PG8_LDB(B1, 0, 1); PG8_SCHED; PG8_LDA(At, 0, 0); PG8_STAGE(PG8_SA(1, 1), a1 + hstepA, voffA);
;             PG8_WAIT_V(8); PG8_WAIT_L(0); PG8_BAR; PG8_MMA(0, 0, At, B0); PG8_MMA(0, 1, At, B1); PG8_BAR; PG8_SCHED;
;             PG8_LDA(At, 0, 1); PG8_STAGE(PG8_SB(0, 0), b2, voffB); PG8_STAGE(PG8_SB(0, 1), b2 + hstepB, voffB); PG8_STAGE(PG8_SA(0, 0), a2, voffA);
;             PG8_WAIT_V(8); PG8_WAIT_L(0); PG8_BAR; PG8_MMA(1, 0, At, B0); PG8_MMA(1, 1, At, B1); PG8_BAR; PG8_SCHED;
.Lpeel3_first:
	s_add_u32 s8, s6, 0xfffc0080
	s_addc_u32 s9, s7, -1
	s_cmp_eq_u32 s69, 12
	s_cselect_b32 s13, s71, s9
	s_cselect_b32 s12, s70, s8
	s_cselect_b32 s15, s73, s51
	s_cselect_b32 s14, s72, s5
	s_add_i32 s81, s63, s36
	ds_read_b128 v[130:133], v222
	ds_read_b128 v[134:137], v222 offset:1024
	ds_read_b128 v[138:141], v222 offset:2048
	ds_read_b128 v[142:145], v222 offset:3072
	ds_read_b128 v[146:149], v223
	ds_read_b128 v[150:153], v223 offset:1024
	ds_read_b128 v[154:157], v223 offset:2048
	ds_read_b128 v[158:161], v223 offset:3072
	s_add_i32 m0, s39, 0xc000
	s_add_i32 s80, s39, 0xe000
	s_add_i32 s82, s81, 0x2000
	s_add_u32 s16, s14, 0x40000
	s_addc_u32 s17, s15, 0
	s_add_i32 s83, s64, s36
	s_add_i32 s84, s83, 0x2000
	s_add_i32 s85, 0, 0x18000
	s_add_i32 s86, 0, 0x1c000
	s_add_u32 s10, s12, 0x40000
	s_addc_u32 s11, s13, 0
	s_add_i32 s75, s85, s36
	s_add_i32 s74, s75, 0x2000
	s_add_u32 s8, s14, 0x40080
	s_addc_u32 s9, s15, 0
	s_add_i32 s79, s86, s36
	s_add_i32 s78, s79, 0x2000
	s_cmp_lg_u32 s69, 12
	ds_read_b128 v[162:165], v224
	ds_read_b128 v[166:169], v224 offset:1024
	ds_read_b128 v[170:173], v224 offset:2048
	ds_read_b128 v[174:177], v224 offset:3072
	ds_read_b128 v[178:181], v224 offset:4096
	ds_read_b128 v[182:185], v224 offset:5120
	ds_read_b128 v[186:189], v224 offset:6144
	ds_read_b128 v[190:193], v224 offset:7168
	global_load_lds_dwordx4 v212, s[6:7]
	s_mov_b32 m0, s80
	s_nop 0
	global_load_lds_dwordx4 v214, s[6:7]
	s_waitcnt vmcnt(8)
	s_waitcnt lgkmcnt(0)
	s_barrier
	s_setprio 1
	s_waitcnt lgkmcnt(0)
	v_mfma_f32_16x16x32_bf16 v[126:129], v[130:133], v[162:165], 0
	v_mfma_f32_16x16x32_bf16 v[118:121], v[138:141], v[162:165], 0
	v_mfma_f32_16x16x32_bf16 v[110:113], v[130:133], v[170:173], 0
	v_mfma_f32_16x16x32_bf16 v[102:105], v[138:141], v[170:173], 0
	v_mfma_f32_16x16x32_bf16 v[94:97], v[130:133], v[178:181], 0
	v_mfma_f32_16x16x32_bf16 v[86:89], v[138:141], v[178:181], 0
	v_mfma_f32_16x16x32_bf16 v[78:81], v[130:133], v[186:189], 0
	v_mfma_f32_16x16x32_bf16 v[70:73], v[138:141], v[186:189], 0
	v_mfma_f32_16x16x32_bf16 v[126:129], v[134:137], v[166:169], v[126:129]
	v_mfma_f32_16x16x32_bf16 v[118:121], v[142:145], v[166:169], v[118:121]
	v_mfma_f32_16x16x32_bf16 v[110:113], v[134:137], v[174:177], v[110:113]
	v_mfma_f32_16x16x32_bf16 v[102:105], v[142:145], v[174:177], v[102:105]
	v_mfma_f32_16x16x32_bf16 v[94:97], v[134:137], v[182:185], v[94:97]
	v_mfma_f32_16x16x32_bf16 v[86:89], v[142:145], v[182:185], v[86:89]
	v_mfma_f32_16x16x32_bf16 v[78:81], v[134:137], v[190:193], v[78:81]
	v_mfma_f32_16x16x32_bf16 v[70:73], v[142:145], v[190:193], v[70:73]
	s_setprio 0
	s_setprio 1
	v_mfma_f32_16x16x32_bf16 v[122:125], v[146:149], v[162:165], 0
	v_mfma_f32_16x16x32_bf16 v[114:117], v[154:157], v[162:165], 0
	v_mfma_f32_16x16x32_bf16 v[106:109], v[146:149], v[170:173], 0
	v_mfma_f32_16x16x32_bf16 v[98:101], v[154:157], v[170:173], 0
	v_mfma_f32_16x16x32_bf16 v[90:93], v[146:149], v[178:181], 0
	v_mfma_f32_16x16x32_bf16 v[82:85], v[154:157], v[178:181], 0
	v_mfma_f32_16x16x32_bf16 v[74:77], v[146:149], v[186:189], 0
	v_mfma_f32_16x16x32_bf16 v[66:69], v[154:157], v[186:189], 0
	v_mfma_f32_16x16x32_bf16 v[122:125], v[150:153], v[166:169], v[122:125]
	v_mfma_f32_16x16x32_bf16 v[114:117], v[158:161], v[166:169], v[114:117]
	v_mfma_f32_16x16x32_bf16 v[106:109], v[150:153], v[174:177], v[106:109]
	v_mfma_f32_16x16x32_bf16 v[98:101], v[158:161], v[174:177], v[98:101]
	v_mfma_f32_16x16x32_bf16 v[90:93], v[150:153], v[182:185], v[90:93]
	v_mfma_f32_16x16x32_bf16 v[82:85], v[158:161], v[182:185], v[82:85]
	v_mfma_f32_16x16x32_bf16 v[74:77], v[150:153], v[190:193], v[74:77]
	v_mfma_f32_16x16x32_bf16 v[66:69], v[158:161], v[190:193], v[66:69]
	s_setprio 0
	s_barrier
	s_mov_b32 m0, s81
	ds_read_b128 v[162:165], v224 offset:16384
	ds_read_b128 v[166:169], v224 offset:17408
	ds_read_b128 v[170:173], v224 offset:18432
	ds_read_b128 v[174:177], v224 offset:19456
	ds_read_b128 v[178:181], v224 offset:20480
	ds_read_b128 v[182:185], v224 offset:21504
	ds_read_b128 v[186:189], v224 offset:22528
	ds_read_b128 v[190:193], v224 offset:23552
	global_load_lds_dwordx4 v202, s[14:15]
	s_mov_b32 m0, s82
	s_nop 0
	global_load_lds_dwordx4 v198, s[14:15]
	s_mov_b32 m0, s83
	s_nop 0
	global_load_lds_dwordx4 v202, s[16:17]
	s_mov_b32 m0, s84
	s_nop 0
	global_load_lds_dwordx4 v198, s[16:17]
	s_mov_b32 m0, s39
	s_nop 0
	global_load_lds_dwordx4 v204, s[12:13]
	s_mov_b32 m0, s40
	s_nop 0
	global_load_lds_dwordx4 v200, s[12:13]
	s_waitcnt vmcnt(8)
	s_waitcnt lgkmcnt(0)
	s_barrier
	s_setprio 1
	s_waitcnt lgkmcnt(0)
	v_mfma_f32_16x16x32_bf16 v[62:65], v[130:133], v[162:165], 0
	v_mfma_f32_16x16x32_bf16 v[54:57], v[138:141], v[162:165], 0
	v_mfma_f32_16x16x32_bf16 v[46:49], v[130:133], v[170:173], 0
	v_mfma_f32_16x16x32_bf16 v[38:41], v[138:141], v[170:173], 0
	v_mfma_f32_16x16x32_bf16 v[30:33], v[130:133], v[178:181], 0
	v_mfma_f32_16x16x32_bf16 v[22:25], v[138:141], v[178:181], 0
	v_mfma_f32_16x16x32_bf16 v[14:17], v[130:133], v[186:189], 0
	v_mfma_f32_16x16x32_bf16 v[6:9], v[138:141], v[186:189], 0
	v_mfma_f32_16x16x32_bf16 v[62:65], v[134:137], v[166:169], v[62:65]
	v_mfma_f32_16x16x32_bf16 v[54:57], v[142:145], v[166:169], v[54:57]
	v_mfma_f32_16x16x32_bf16 v[46:49], v[134:137], v[174:177], v[46:49]
	v_mfma_f32_16x16x32_bf16 v[38:41], v[142:145], v[174:177], v[38:41]
	v_mfma_f32_16x16x32_bf16 v[30:33], v[134:137], v[182:185], v[30:33]
	v_mfma_f32_16x16x32_bf16 v[22:25], v[142:145], v[182:185], v[22:25]
	v_mfma_f32_16x16x32_bf16 v[14:17], v[134:137], v[190:193], v[14:17]
	v_mfma_f32_16x16x32_bf16 v[6:9], v[142:145], v[190:193], v[6:9]
	s_setprio 0
	s_setprio 1
	v_mfma_f32_16x16x32_bf16 v[58:61], v[146:149], v[162:165], 0
	v_mfma_f32_16x16x32_bf16 v[50:53], v[154:157], v[162:165], 0
	v_mfma_f32_16x16x32_bf16 v[42:45], v[146:149], v[170:173], 0
	v_mfma_f32_16x16x32_bf16 v[34:37], v[154:157], v[170:173], 0
	v_mfma_f32_16x16x32_bf16 v[26:29], v[146:149], v[178:181], 0
	v_mfma_f32_16x16x32_bf16 v[18:21], v[154:157], v[178:181], 0
	v_mfma_f32_16x16x32_bf16 v[10:13], v[146:149], v[186:189], 0
	v_mfma_f32_16x16x32_bf16 v[2:5], v[154:157], v[186:189], 0
	v_mfma_f32_16x16x32_bf16 v[58:61], v[150:153], v[166:169], v[58:61]
	v_mfma_f32_16x16x32_bf16 v[50:53], v[158:161], v[166:169], v[50:53]
	v_mfma_f32_16x16x32_bf16 v[42:45], v[150:153], v[174:177], v[42:45]
	v_mfma_f32_16x16x32_bf16 v[34:37], v[158:161], v[174:177], v[34:37]
	v_mfma_f32_16x16x32_bf16 v[26:29], v[150:153], v[182:185], v[26:29]
	v_mfma_f32_16x16x32_bf16 v[18:21], v[158:161], v[182:185], v[18:21]
	v_mfma_f32_16x16x32_bf16 v[10:13], v[150:153], v[190:193], v[10:13]
	v_mfma_f32_16x16x32_bf16 v[2:5], v[158:161], v[190:193], v[2:5]
	s_setprio 0
	s_barrier
	s_branch .Lpeel3_join

; #define PG8_STAGE(bufoff, gbase, voff) do { _Pragma("unroll") for (int _i = 0; _i < 2; ++_i) \
;         __builtin_amdgcn_global_load_lds((const unsigned*)((const char*)(gbase) + (voff)[_i]), (LAS unsigned*)(lds + (bufoff) + ldsw + _i * 8192), 16, 0, 0); } while (0)
; #define PG8_LDA(dst, b, h) do { _Pragma("unroll") for (int m = 0; m < 4; ++m) _Pragma("unroll") for (int k = 0; k < 2; ++k) dst[m][k] = *(const LAS bf16x8*)(lds + PG8_SA(b, h) + aoff + m * 2048 + k * 1024); } while (0)
; #define PG8_LDB(dst, b, h) do { _Pragma("unroll") for (int n = 0; n < 2; ++n) _Pragma("unroll") for (int k = 0; k < 2; ++k) dst[n][k] = *(const LAS bf16x8*)(lds + PG8_SB(b, h) + boff + n * 2048 + k * 1024); } while (0)
; #define PG8_MMA(ai, bj, At, Bt) do { __builtin_amdgcn_s_setprio(1); _Pragma("unroll") for (int m = 0; m < 4; ++m) _Pragma("unroll") for (int n = 0; n < 2; ++n) _Pragma("unroll") for (int k = 0; k < 2; ++k) \
;         acc[ai][bj][m][n] = __builtin_amdgcn_mfma_f32_16x16x32_bf16(Bt[n][k], At[m][k], acc[ai][bj][m][n], 0, 0, 0); __builtin_amdgcn_s_setprio(0); } while (0)
; #define PG8_WAIT_V(n) asm volatile("s_waitcnt vmcnt(" #n ")" ::: "memory")
; template <class Epi, class Sched>
; __device__ __forceinline__ void gemm_phase(LAS unsigned char* lds, const int lda, const int ldb, const int K, const Sched& S, const Epi& E) {
;     ...
;         const bool has_next = S.next(ui + 1, nxt);
;         const char* nA = has_next ? nxt.A : cA; const char* nB = has_next ? nxt.B : cB;
;         for (int t = 0; t < nt; t += 2) {
;             const bool last = (t == nt - 2);
;             const char* a1 = cA + (size_t)(t + 1) * kstep;
;             const char* a2 = last ? nA : cA + (size_t)(t + 2) * kstep; const char* b2 = last ? nB : cB + (size_t)(t + 2) * kstep;
;             const char* a3 = a2 + kstep; const char* b3 = b2 + kstep;
;             PG8_LDB(B0, 0, 0); PG8_LDB(B1, 0, 1); PG8_SCHED; PG8_LDA(At, 0, 0); PG8_STAGE(PG8_SA(1, 1), a1 + hstepA, voffA);
;             PG8_WAIT_V(8); PG8_WAIT_L(0); PG8_BAR; PG8_MMA(0, 0, At, B0); PG8_MMA(0, 1, At, B1); PG8_BAR; PG8_SCHED;
;             PG8_LDA(At, 0, 1); PG8_STAGE(PG8_SB(0, 0), b2, voffB); PG8_STAGE(PG8_SB(0, 1), b2 + hstepB, voffB); PG8_STAGE(PG8_SA(0, 0), a2, voffA);
;             PG8_WAIT_V(8); PG8_WAIT_L(0); PG8_BAR; PG8_MMA(1, 0, At, B0); PG8_MMA(1, 1, At, B1); PG8_BAR; PG8_SCHED;
.LBB0_1052:
	s_lshl_b32 s20, s20, 8
	s_ashr_i32 s21, s20, 31
	s_add_u32 s22, s22, 0x40080
	s_addc_u32 s23, s23, 0
	s_add_u32 s13, s24, 0x100
	v_lshl_add_u64 v[214:215], s[20:21], 2, v[204:205]
	s_addc_u32 s15, s25, 0
	s_mov_b32 s21, -2
	v_add_u32_e32 v230, 0x80, v200
	v_add_u32_e32 v231, 0x80, v196
	v_add_u32_e32 v232, 0x80, v202
	v_add_u32_e32 v233, 0x80, v198
	s_cmp_eq_u32 s43, 1
	s_cbranch_scc1 .Lpeel6_first
	s_add_u32 s24, s22, 0xfffc0080
	s_addc_u32 s25, s23, -1
	s_cmp_eq_u32 s21, 12
	s_cselect_b32 s29, s17, s25
	s_cselect_b32 s28, s16, s24
	s_cselect_b32 s31, s19, s15
	s_cselect_b32 s30, s18, s13
	s_add_i32 s70, s50, s36
	ds_read_b128 v[130:133], v217
	ds_read_b128 v[134:137], v217 offset:1024
	ds_read_b128 v[138:141], v217 offset:2048
	ds_read_b128 v[142:145], v217 offset:3072
	ds_read_b128 v[146:149], v218
	ds_read_b128 v[150:153], v218 offset:1024
	ds_read_b128 v[154:157], v218 offset:2048
	ds_read_b128 v[158:161], v218 offset:3072
	s_add_i32 m0, s39, 0xc000
	s_add_i32 s69, s39, 0xe000
	s_add_i32 s71, s70, 0x2000
	s_add_u32 s34, s30, 0x40000
	s_addc_u32 s35, s31, 0
	s_add_i32 s72, s51, s36
	s_add_i32 s73, s72, 0x2000
	s_add_i32 s74, 0, 0x18000
	s_add_i32 s75, 0, 0x1c000
	s_add_u32 s26, s28, 0x40000
	s_addc_u32 s27, s29, 0
	s_add_i32 s66, s74, s36
	s_add_i32 s65, s66, 0x2000
	s_add_u32 s24, s30, 0x40080
	s_addc_u32 s25, s31, 0
	s_add_i32 s68, s75, s36
	s_add_i32 s67, s68, 0x2000
	s_cmp_lg_u32 s21, 12
	ds_read_b128 v[162:165], v219
	ds_read_b128 v[166:169], v219 offset:1024
	ds_read_b128 v[170:173], v219 offset:2048
	ds_read_b128 v[174:177], v219 offset:3072
	ds_read_b128 v[178:181], v219 offset:4096
	ds_read_b128 v[182:185], v219 offset:5120
	ds_read_b128 v[186:189], v219 offset:6144
	ds_read_b128 v[190:193], v219 offset:7168
	global_load_lds_dwordx4 v206, s[22:23]
	s_mov_b32 m0, s69
	s_nop 0
	global_load_lds_dwordx4 v208, s[22:23]
	s_waitcnt vmcnt(16)
	s_waitcnt lgkmcnt(0)
	s_barrier
	s_setprio 1
	s_waitcnt lgkmcnt(0)
	v_mfma_f32_16x16x32_bf16 v[126:129], v[130:133], v[162:165], 0
	v_mfma_f32_16x16x32_bf16 v[118:121], v[138:141], v[162:165], 0
	v_mfma_f32_16x16x32_bf16 v[110:113], v[130:133], v[170:173], 0
	v_mfma_f32_16x16x32_bf16 v[102:105], v[138:141], v[170:173], 0
	v_mfma_f32_16x16x32_bf16 v[94:97], v[130:133], v[178:181], 0
	v_mfma_f32_16x16x32_bf16 v[86:89], v[138:141], v[178:181], 0
	v_mfma_f32_16x16x32_bf16 v[78:81], v[130:133], v[186:189], 0
	v_mfma_f32_16x16x32_bf16 v[70:73], v[138:141], v[186:189], 0
	v_mfma_f32_16x16x32_bf16 v[126:129], v[134:137], v[166:169], v[126:129]
	v_mfma_f32_16x16x32_bf16 v[118:121], v[142:145], v[166:169], v[118:121]
	v_mfma_f32_16x16x32_bf16 v[110:113], v[134:137], v[174:177], v[110:113]
	v_mfma_f32_16x16x32_bf16 v[102:105], v[142:145], v[174:177], v[102:105]
	v_mfma_f32_16x16x32_bf16 v[94:97], v[134:137], v[182:185], v[94:97]
	v_mfma_f32_16x16x32_bf16 v[86:89], v[142:145], v[182:185], v[86:89]
	v_mfma_f32_16x16x32_bf16 v[78:81], v[134:137], v[190:193], v[78:81]
	v_mfma_f32_16x16x32_bf16 v[70:73], v[142:145], v[190:193], v[70:73]
	s_setprio 0
	s_setprio 1
	v_mfma_f32_16x16x32_bf16 v[122:125], v[146:149], v[162:165], 0
	v_mfma_f32_16x16x32_bf16 v[114:117], v[154:157], v[162:165], 0
	v_mfma_f32_16x16x32_bf16 v[106:109], v[146:149], v[170:173], 0
	v_mfma_f32_16x16x32_bf16 v[98:101], v[154:157], v[170:173], 0
	v_mfma_f32_16x16x32_bf16 v[90:93], v[146:149], v[178:181], 0
	v_mfma_f32_16x16x32_bf16 v[82:85], v[154:157], v[178:181], 0
	v_mfma_f32_16x16x32_bf16 v[74:77], v[146:149], v[186:189], 0
	v_mfma_f32_16x16x32_bf16 v[66:69], v[154:157], v[186:189], 0
	v_mfma_f32_16x16x32_bf16 v[122:125], v[150:153], v[166:169], v[122:125]
	v_mfma_f32_16x16x32_bf16 v[114:117], v[158:161], v[166:169], v[114:117]
	v_mfma_f32_16x16x32_bf16 v[106:109], v[150:153], v[174:177], v[106:109]
	v_mfma_f32_16x16x32_bf16 v[98:101], v[158:161], v[174:177], v[98:101]
	v_mfma_f32_16x16x32_bf16 v[90:93], v[150:153], v[182:185], v[90:93]
	v_mfma_f32_16x16x32_bf16 v[82:85], v[158:161], v[182:185], v[82:85]
	v_mfma_f32_16x16x32_bf16 v[74:77], v[150:153], v[190:193], v[74:77]
	v_mfma_f32_16x16x32_bf16 v[66:69], v[158:161], v[190:193], v[66:69]
	s_setprio 0
	s_barrier
	s_mov_b32 m0, s70
	ds_read_b128 v[162:165], v219 offset:16384
	ds_read_b128 v[166:169], v219 offset:17408
	ds_read_b128 v[170:173], v219 offset:18432
	ds_read_b128 v[174:177], v219 offset:19456
	ds_read_b128 v[178:181], v219 offset:20480
	ds_read_b128 v[182:185], v219 offset:21504
	ds_read_b128 v[186:189], v219 offset:22528
	ds_read_b128 v[190:193], v219 offset:23552
	global_load_lds_dwordx4 v200, s[30:31]
	s_mov_b32 m0, s71
	s_nop 0
	global_load_lds_dwordx4 v196, s[30:31]
	s_mov_b32 m0, s72
	s_nop 0
	global_load_lds_dwordx4 v200, s[34:35]
	s_mov_b32 m0, s73
	s_nop 0
	global_load_lds_dwordx4 v196, s[34:35]
	s_mov_b32 m0, s39
	s_nop 0
	global_load_lds_dwordx4 v202, s[28:29]
	s_mov_b32 m0, s40
	s_nop 0
	global_load_lds_dwordx4 v198, s[28:29]
	s_waitcnt vmcnt(16)
	s_waitcnt lgkmcnt(0)
	s_barrier
; #define PG8_STAGE(bufoff, gbase, voff) do { _Pragma("unroll") for (int _i = 0; _i < 2; ++_i) \
;         __builtin_amdgcn_global_load_lds((const unsigned*)((const char*)(gbase) + (voff)[_i]), (LAS unsigned*)(lds + (bufoff) + ldsw + _i * 8192), 16, 0, 0); } while (0)
; #define PG8_LDA(dst, b, h) do { _Pragma("unroll") for (int m = 0; m < 4; ++m) _Pragma("unroll") for (int k = 0; k < 2; ++k) dst[m][k] = *(const LAS bf16x8*)(lds + PG8_SA(b, h) + aoff + m * 2048 + k * 1024); } while (0)
; #define PG8_MMA(ai, bj, At, Bt) do { __builtin_amdgcn_s_setprio(1); _Pragma("unroll") for (int m = 0; m < 4; ++m) _Pragma("unroll") for (int n = 0; n < 2; ++n) _Pragma("unroll") for (int k = 0; k < 2; ++k) \
;         acc[ai][bj][m][n] = __builtin_amdgcn_mfma_f32_16x16x32_bf16(Bt[n][k], At[m][k], acc[ai][bj][m][n], 0, 0, 0); __builtin_amdgcn_s_setprio(0); } while (0)
; #define PG8_WAIT_V(n) asm volatile("s_waitcnt vmcnt(" #n ")" ::: "memory")
; #define PG8_WAIT_L(n) asm volatile("s_waitcnt lgkmcnt(" #n ")" ::: "memory")
; #define PG8_BAR __builtin_amdgcn_s_barrier()
; #define PG8_SCHED __builtin_amdgcn_sched_barrier(0)
; template <class Epi, class Sched>
; __device__ __forceinline__ void gemm_phase(LAS unsigned char* lds, const int lda, const int ldb, const int K, const Sched& S, const Epi& E) {
;     ...
;             PG8_WAIT_V(8); PG8_WAIT_L(0); PG8_BAR; PG8_MMA(0, 0, At, B0); PG8_MMA(0, 1, At, B1); PG8_BAR; PG8_SCHED;
;             PG8_LDA(At, 0, 1); PG8_STAGE(PG8_SB(0, 0), b2, voffB); PG8_STAGE(PG8_SB(0, 1), b2 + hstepB, voffB); PG8_STAGE(PG8_SA(0, 0), a2, voffA);
;             PG8_WAIT_V(8); PG8_WAIT_L(0); PG8_BAR; PG8_MMA(1, 0, At, B0); PG8_MMA(1, 1, At, B1); PG8_BAR; PG8_SCHED;
	s_setprio 1
	s_waitcnt lgkmcnt(0)
	v_mfma_f32_16x16x32_bf16 v[62:65], v[130:133], v[162:165], 0
	v_mfma_f32_16x16x32_bf16 v[54:57], v[138:141], v[162:165], 0
	v_mfma_f32_16x16x32_bf16 v[46:49], v[130:133], v[170:173], 0
	v_mfma_f32_16x16x32_bf16 v[38:41], v[138:141], v[170:173], 0
	v_mfma_f32_16x16x32_bf16 v[30:33], v[130:133], v[178:181], 0
	v_mfma_f32_16x16x32_bf16 v[22:25], v[138:141], v[178:181], 0
	v_mfma_f32_16x16x32_bf16 v[14:17], v[130:133], v[186:189], 0
	v_mfma_f32_16x16x32_bf16 v[6:9], v[138:141], v[186:189], 0
	v_mfma_f32_16x16x32_bf16 v[62:65], v[134:137], v[166:169], v[62:65]
	v_mfma_f32_16x16x32_bf16 v[54:57], v[142:145], v[166:169], v[54:57]
	v_mfma_f32_16x16x32_bf16 v[46:49], v[134:137], v[174:177], v[46:49]
	v_mfma_f32_16x16x32_bf16 v[38:41], v[142:145], v[174:177], v[38:41]
	v_mfma_f32_16x16x32_bf16 v[30:33], v[134:137], v[182:185], v[30:33]
	v_mfma_f32_16x16x32_bf16 v[22:25], v[142:145], v[182:185], v[22:25]
	v_mfma_f32_16x16x32_bf16 v[14:17], v[134:137], v[190:193], v[14:17]
	v_mfma_f32_16x16x32_bf16 v[6:9], v[142:145], v[190:193], v[6:9]
	s_setprio 0
	s_setprio 1
	v_mfma_f32_16x16x32_bf16 v[58:61], v[146:149], v[162:165], 0
	v_mfma_f32_16x16x32_bf16 v[50:53], v[154:157], v[162:165], 0
	v_mfma_f32_16x16x32_bf16 v[42:45], v[146:149], v[170:173], 0
	v_mfma_f32_16x16x32_bf16 v[34:37], v[154:157], v[170:173], 0
	v_mfma_f32_16x16x32_bf16 v[26:29], v[146:149], v[178:181], 0
	v_mfma_f32_16x16x32_bf16 v[18:21], v[154:157], v[178:181], 0
	v_mfma_f32_16x16x32_bf16 v[10:13], v[146:149], v[186:189], 0
	v_mfma_f32_16x16x32_bf16 v[2:5], v[154:157], v[186:189], 0
	v_mfma_f32_16x16x32_bf16 v[58:61], v[150:153], v[166:169], v[58:61]
	v_mfma_f32_16x16x32_bf16 v[50:53], v[158:161], v[166:169], v[50:53]
	v_mfma_f32_16x16x32_bf16 v[42:45], v[150:153], v[174:177], v[42:45]
	v_mfma_f32_16x16x32_bf16 v[34:37], v[158:161], v[174:177], v[34:37]
	v_mfma_f32_16x16x32_bf16 v[26:29], v[150:153], v[182:185], v[26:29]
	v_mfma_f32_16x16x32_bf16 v[18:21], v[158:161], v[182:185], v[18:21]
	v_mfma_f32_16x16x32_bf16 v[10:13], v[150:153], v[190:193], v[10:13]
	v_mfma_f32_16x16x32_bf16 v[2:5], v[158:161], v[190:193], v[2:5]
	s_setprio 0
	s_barrier
	s_branch .Lpeel6_join
; #define PG8_STAGE(bufoff, gbase, voff) do { _Pragma("unroll") for (int _i = 0; _i < 2; ++_i) \
;         __builtin_amdgcn_global_load_lds((const unsigned*)((const char*)(gbase) + (voff)[_i]), (LAS unsigned*)(lds + (bufoff) + ldsw + _i * 8192), 16, 0, 0); } while (0)
; #define PG8_LDA(dst, b, h) do { _Pragma("unroll") for (int m = 0; m < 4; ++m) _Pragma("unroll") for (int k = 0; k < 2; ++k) dst[m][k] = *(const LAS bf16x8*)(lds + PG8_SA(b, h) + aoff + m * 2048 + k * 1024); } while (0)
; #define PG8_LDB(dst, b, h) do { _Pragma("unroll") for (int n = 0; n < 2; ++n) _Pragma("unroll") for (int k = 0; k < 2; ++k) dst[n][k] = *(const LAS bf16x8*)(lds + PG8_SB(b, h) + boff + n * 2048 + k * 1024); } while (0)
; #define PG8_MMA(ai, bj, At, Bt) do { __builtin_amdgcn_s_setprio(1); _Pragma("unroll") for (int m = 0; m < 4; ++m) _Pragma("unroll") for (int n = 0; n < 2; ++n) _Pragma("unroll") for (int k = 0; k < 2; ++k) \
;         acc[ai][bj][m][n] = __builtin_amdgcn_mfma_f32_16x16x32_bf16(Bt[n][k], At[m][k], acc[ai][bj][m][n], 0, 0, 0); __builtin_amdgcn_s_setprio(0); } while (0)
; #define PG8_WAIT_V(n) asm volatile("s_waitcnt vmcnt(" #n ")" ::: "memory")
; template <class Epi, class Sched>
; __device__ __forceinline__ void gemm_phase(LAS unsigned char* lds, const int lda, const int ldb, const int K, const Sched& S, const Epi& E) {
;     ...
;         const bool has_next = S.next(ui + 1, nxt);
;         const char* nA = has_next ? nxt.A : cA; const char* nB = has_next ? nxt.B : cB;
;         for (int t = 0; t < nt; t += 2) {
;             const bool last = (t == nt - 2);
;             const char* a1 = cA + (size_t)(t + 1) * kstep;
;             const char* a2 = last ? nA : cA + (size_t)(t + 2) * kstep; const char* b2 = last ? nB : cB + (size_t)(t + 2) * kstep;
;             const char* a3 = a2 + kstep; const char* b3 = b2 + kstep;
;             PG8_LDB(B0, 0, 0); PG8_LDB(B1, 0, 1); PG8_SCHED; PG8_LDA(At, 0, 0); PG8_STAGE(PG8_SA(1, 1), a1 + hstepA, voffA);
;             PG8_WAIT_V(8); PG8_WAIT_L(0); PG8_BAR; PG8_MMA(0, 0, At, B0); PG8_MMA(0, 1, At, B1); PG8_BAR; PG8_SCHED;
;             PG8_LDA(At, 0, 1); PG8_STAGE(PG8_SB(0, 0), b2, voffB); PG8_STAGE(PG8_SB(0, 1), b2 + hstepB, voffB); PG8_STAGE(PG8_SA(0, 0), a2, voffA);
;             PG8_WAIT_V(8); PG8_WAIT_L(0); PG8_BAR; PG8_MMA(1, 0, At, B0); PG8_MMA(1, 1, At, B1); PG8_BAR; PG8_SCHED;
.Lpeel6_first:
	s_add_u32 s24, s22, 0xfffc0080
	s_addc_u32 s25, s23, -1
	s_cmp_eq_u32 s21, 12
	s_cselect_b32 s29, s17, s25
	s_cselect_b32 s28, s16, s24
	s_cselect_b32 s31, s19, s15
	s_cselect_b32 s30, s18, s13
	s_add_i32 s70, s50, s36
	ds_read_b128 v[130:133], v217
	ds_read_b128 v[134:137], v217 offset:1024
	ds_read_b128 v[138:141], v217 offset:2048
	ds_read_b128 v[142:145], v217 offset:3072
	ds_read_b128 v[146:149], v218
	ds_read_b128 v[150:153], v218 offset:1024
	ds_read_b128 v[154:157], v218 offset:2048
	ds_read_b128 v[158:161], v218 offset:3072
	s_add_i32 m0, s39, 0xc000
	s_add_i32 s69, s39, 0xe000
	s_add_i32 s71, s70, 0x2000
	s_add_u32 s34, s30, 0x40000
	s_addc_u32 s35, s31, 0
	s_add_i32 s72, s51, s36
	s_add_i32 s73, s72, 0x2000
	s_add_i32 s74, 0, 0x18000
	s_add_i32 s75, 0, 0x1c000
	s_add_u32 s26, s28, 0x40000
	s_addc_u32 s27, s29, 0
	s_add_i32 s66, s74, s36
	s_add_i32 s65, s66, 0x2000
	s_add_u32 s24, s30, 0x40080
	s_addc_u32 s25, s31, 0
	s_add_i32 s68, s75, s36
	s_add_i32 s67, s68, 0x2000
	s_cmp_lg_u32 s21, 12
	ds_read_b128 v[162:165], v219
	ds_read_b128 v[166:169], v219 offset:1024
	ds_read_b128 v[170:173], v219 offset:2048
	ds_read_b128 v[174:177], v219 offset:3072
	ds_read_b128 v[178:181], v219 offset:4096
	ds_read_b128 v[182:185], v219 offset:5120
	ds_read_b128 v[186:189], v219 offset:6144
	ds_read_b128 v[190:193], v219 offset:7168
	global_load_lds_dwordx4 v206, s[22:23]
	s_mov_b32 m0, s69
	s_nop 0
	global_load_lds_dwordx4 v208, s[22:23]
	s_waitcnt vmcnt(8)
	s_waitcnt lgkmcnt(0)
	s_barrier
	s_setprio 1
	s_waitcnt lgkmcnt(0)
	v_mfma_f32_16x16x32_bf16 v[126:129], v[130:133], v[162:165], 0
	v_mfma_f32_16x16x32_bf16 v[118:121], v[138:141], v[162:165], 0
	v_mfma_f32_16x16x32_bf16 v[110:113], v[130:133], v[170:173], 0
	v_mfma_f32_16x16x32_bf16 v[102:105], v[138:141], v[170:173], 0
	v_mfma_f32_16x16x32_bf16 v[94:97], v[130:133], v[178:181], 0
	v_mfma_f32_16x16x32_bf16 v[86:89], v[138:141], v[178:181], 0
	v_mfma_f32_16x16x32_bf16 v[78:81], v[130:133], v[186:189], 0
	v_mfma_f32_16x16x32_bf16 v[70:73], v[138:141], v[186:189], 0
	v_mfma_f32_16x16x32_bf16 v[126:129], v[134:137], v[166:169], v[126:129]
	v_mfma_f32_16x16x32_bf16 v[118:121], v[142:145], v[166:169], v[118:121]
	v_mfma_f32_16x16x32_bf16 v[110:113], v[134:137], v[174:177], v[110:113]
	v_mfma_f32_16x16x32_bf16 v[102:105], v[142:145], v[174:177], v[102:105]
	v_mfma_f32_16x16x32_bf16 v[94:97], v[134:137], v[182:185], v[94:97]
	v_mfma_f32_16x16x32_bf16 v[86:89], v[142:145], v[182:185], v[86:89]
	v_mfma_f32_16x16x32_bf16 v[78:81], v[134:137], v[190:193], v[78:81]
	v_mfma_f32_16x16x32_bf16 v[70:73], v[142:145], v[190:193], v[70:73]
	s_setprio 0
	s_setprio 1
	v_mfma_f32_16x16x32_bf16 v[122:125], v[146:149], v[162:165], 0
	v_mfma_f32_16x16x32_bf16 v[114:117], v[154:157], v[162:165], 0
	v_mfma_f32_16x16x32_bf16 v[106:109], v[146:149], v[170:173], 0
	v_mfma_f32_16x16x32_bf16 v[98:101], v[154:157], v[170:173], 0
	v_mfma_f32_16x16x32_bf16 v[90:93], v[146:149], v[178:181], 0
	v_mfma_f32_16x16x32_bf16 v[82:85], v[154:157], v[178:181], 0
	v_mfma_f32_16x16x32_bf16 v[74:77], v[146:149], v[186:189], 0
	v_mfma_f32_16x16x32_bf16 v[66:69], v[154:157], v[186:189], 0
	v_mfma_f32_16x16x32_bf16 v[122:125], v[150:153], v[166:169], v[122:125]
	v_mfma_f32_16x16x32_bf16 v[114:117], v[158:161], v[166:169], v[114:117]
	v_mfma_f32_16x16x32_bf16 v[106:109], v[150:153], v[174:177], v[106:109]
	v_mfma_f32_16x16x32_bf16 v[98:101], v[158:161], v[174:177], v[98:101]
	v_mfma_f32_16x16x32_bf16 v[90:93], v[150:153], v[182:185], v[90:93]
	v_mfma_f32_16x16x32_bf16 v[82:85], v[158:161], v[182:185], v[82:85]
	v_mfma_f32_16x16x32_bf16 v[74:77], v[150:153], v[190:193], v[74:77]
	v_mfma_f32_16x16x32_bf16 v[66:69], v[158:161], v[190:193], v[66:69]
	s_setprio 0
	s_barrier
	s_mov_b32 m0, s70
	ds_read_b128 v[162:165], v219 offset:16384
	ds_read_b128 v[166:169], v219 offset:17408
	ds_read_b128 v[170:173], v219 offset:18432
	ds_read_b128 v[174:177], v219 offset:19456
	ds_read_b128 v[178:181], v219 offset:20480
	ds_read_b128 v[182:185], v219 offset:21504
	ds_read_b128 v[186:189], v219 offset:22528
	ds_read_b128 v[190:193], v219 offset:23552
	global_load_lds_dwordx4 v200, s[30:31]
	s_mov_b32 m0, s71
	s_nop 0
	global_load_lds_dwordx4 v196, s[30:31]
	s_mov_b32 m0, s72
	s_nop 0
	global_load_lds_dwordx4 v200, s[34:35]
	s_mov_b32 m0, s73
	s_nop 0
	global_load_lds_dwordx4 v196, s[34:35]
	s_mov_b32 m0, s39
	s_nop 0
	global_load_lds_dwordx4 v202, s[28:29]
	s_mov_b32 m0, s40
	s_nop 0
	global_load_lds_dwordx4 v198, s[28:29]
	s_waitcnt vmcnt(8)
	s_waitcnt lgkmcnt(0)
	s_barrier
	s_setprio 1
	s_waitcnt lgkmcnt(0)
	v_mfma_f32_16x16x32_bf16 v[62:65], v[130:133], v[162:165], 0
	v_mfma_f32_16x16x32_bf16 v[54:57], v[138:141], v[162:165], 0
	v_mfma_f32_16x16x32_bf16 v[46:49], v[130:133], v[170:173], 0
	v_mfma_f32_16x16x32_bf16 v[38:41], v[138:141], v[170:173], 0
	v_mfma_f32_16x16x32_bf16 v[30:33], v[130:133], v[178:181], 0
	v_mfma_f32_16x16x32_bf16 v[22:25], v[138:141], v[178:181], 0
	v_mfma_f32_16x16x32_bf16 v[14:17], v[130:133], v[186:189], 0
	v_mfma_f32_16x16x32_bf16 v[6:9], v[138:141], v[186:189], 0
	v_mfma_f32_16x16x32_bf16 v[62:65], v[134:137], v[166:169], v[62:65]
	v_mfma_f32_16x16x32_bf16 v[54:57], v[142:145], v[166:169], v[54:57]
	v_mfma_f32_16x16x32_bf16 v[46:49], v[134:137], v[174:177], v[46:49]
	v_mfma_f32_16x16x32_bf16 v[38:41], v[142:145], v[174:177], v[38:41]
	v_mfma_f32_16x16x32_bf16 v[30:33], v[134:137], v[182:185], v[30:33]
	v_mfma_f32_16x16x32_bf16 v[22:25], v[142:145], v[182:185], v[22:25]
	v_mfma_f32_16x16x32_bf16 v[14:17], v[134:137], v[190:193], v[14:17]
	v_mfma_f32_16x16x32_bf16 v[6:9], v[142:145], v[190:193], v[6:9]
	s_setprio 0
	s_setprio 1
	v_mfma_f32_16x16x32_bf16 v[58:61], v[146:149], v[162:165], 0
	v_mfma_f32_16x16x32_bf16 v[50:53], v[154:157], v[162:165], 0
	v_mfma_f32_16x16x32_bf16 v[42:45], v[146:149], v[170:173], 0
	v_mfma_f32_16x16x32_bf16 v[34:37], v[154:157], v[170:173], 0
	v_mfma_f32_16x16x32_bf16 v[26:29], v[146:149], v[178:181], 0
	v_mfma_f32_16x16x32_bf16 v[18:21], v[154:157], v[178:181], 0
	v_mfma_f32_16x16x32_bf16 v[10:13], v[146:149], v[186:189], 0
	v_mfma_f32_16x16x32_bf16 v[2:5], v[154:157], v[186:189], 0
	v_mfma_f32_16x16x32_bf16 v[58:61], v[150:153], v[166:169], v[58:61]
	v_mfma_f32_16x16x32_bf16 v[50:53], v[158:161], v[166:169], v[50:53]
	v_mfma_f32_16x16x32_bf16 v[42:45], v[150:153], v[174:177], v[42:45]
	v_mfma_f32_16x16x32_bf16 v[34:37], v[158:161], v[174:177], v[34:37]
	v_mfma_f32_16x16x32_bf16 v[26:29], v[150:153], v[182:185], v[26:29]
	v_mfma_f32_16x16x32_bf16 v[18:21], v[158:161], v[182:185], v[18:21]
	v_mfma_f32_16x16x32_bf16 v[10:13], v[150:153], v[190:193], v[10:13]
	v_mfma_f32_16x16x32_bf16 v[2:5], v[158:161], v[190:193], v[2:5]
	s_setprio 0
	s_barrier
	s_branch .Lpeel6_join
